# P3: one static s_setprio 1 for waves 4-7 during the retention phase
# speedup vs baseline: 1.0078x; 1.0008x over previous
.LBB0_585:
	v_readlane_b32 s0, v255, 2
	v_readlane_b32 s1, v255, 3
	s_mov_b64 s[4:5], s[0:1]
	s_cmp_lt_i32 s4, 4
	v_readlane_b32 s2, v255, 4
	v_readlane_b32 s3, v255, 5
	s_cselect_b64 s[0:1], -1, 0
	s_cmp_gt_i32 s5, 3
	s_cselect_b64 s[2:3], -1, 0
	s_and_b64 s[0:1], s[0:1], s[2:3]
	v_writelane_b32 v255, s0, 9
	s_andn2_b64 vcc, exec, s[0:1]
	s_nop 0
	v_writelane_b32 v255, s1, 10
	s_cbranch_vccnz .LBB0_617
	s_mov_b64 s[2:3], s[74:75]
	v_mov_b32_e32 v1, v0
	s_cmpk_gt_i32 s84, 0xff
	s_cbranch_scc1 .LBB0_617
	v_readfirstlane_b32 s98, v0
	s_nop 1
	s_lshr_b32 s98, s98, 6
	s_cmp_lt_u32 s98, 4
	s_cbranch_scc1 .Lmy_p3_noprio
	s_setprio 1
.Lmy_p3_noprio:
	s_load_dwordx2 s[82:83], s[2:3], 0x88
	v_writelane_b32 v255, s90, 11
	v_writelane_b32 v255, s74, 12
	v_lshrrev_b32_e32 v156, 3, v0
	v_xor_b32_e32 v9, 0x7f, v156
	s_waitcnt lgkmcnt(0)
	s_add_u32 s0, s82, 0x7a00000
	s_addc_u32 s1, s83, 0
	v_writelane_b32 v255, s75, 13
	s_add_u32 s86, s82, 0xba00000
	v_writelane_b32 v255, s91, 14
	s_addc_u32 s87, s83, 0
	v_writelane_b32 v255, s0, 15
	s_add_u32 s88, s82, 0xfa00000
	v_bfe_u32 v3, v0, 5, 1
	v_writelane_b32 v255, s1, 16
	s_addc_u32 s89, s83, 0
	v_cvt_f32_ubyte0_e32 v159, v9
	v_xor_b32_e32 v9, 63, v156
	s_add_i32 s0, 0, 0x11000
	v_and_b32_e32 v11, 12, v0
	s_movk_i32 s93, 0x110
	v_cvt_f32_ubyte0_e32 v194, v9
	s_movk_i32 s1, 0x90
	v_mov_b32_e32 v9, s0
	v_lshl_or_b32 v11, v3, 1, v11
	v_mad_u32_u24 v196, v11, s93, 0
	v_mad_u32_u24 v197, v11, s1, v9
	v_bfe_u32 v11, v0, 2, 2
	v_and_b32_e32 v1, 31, v0
	v_lshrrev_b32_e32 v2, 2, v0
	v_lshrrev_b32_e32 v154, 4, v0
	v_and_b32_e32 v5, 15, v0
	v_and_b32_e32 v7, 7, v0
	v_lshlrev_b32_e32 v12, 2, v0
	v_lshl_or_b32 v11, v3, 3, v11
	v_lshlrev_b32_e32 v155, 2, v3
	v_and_b32_e32 v157, 8, v2
	v_mov_b32_e32 v2, 0
	v_lshlrev_b32_e32 v4, 3, v5
	v_lshlrev_b32_e32 v6, 3, v7
	v_lshlrev_b32_e32 v5, 4, v5
	v_mad_u32_u24 v8, v154, s93, 0
	v_lshlrev_b32_e32 v7, 4, v7
	v_mad_u32_u24 v10, v156, s1, v9
	v_lshlrev_b32_e32 v158, 4, v3
	v_and_b32_e32 v12, 12, v12
	v_mad_u32_u24 v200, v11, s1, v9
	s_add_i32 s0, 0, 0x15800
	v_lshlrev_b32_e32 v9, 1, v1
	s_mov_b32 s91, 0
	v_add_u32_e32 v195, 0, v158
	v_or_b32_e32 v199, 32, v1
	v_and_or_b32 v201, v0, 16, v12
	v_cmp_eq_u32_e64 s[2:3], 31, v1
	v_lshlrev_b32_e32 v160, 10, v3
	v_or_b32_e32 v252, 1, v155
	v_or_b32_e32 v253, 2, v155
	v_or_b32_e32 v254, 3, v155
	v_or_b32_e32 v198, 8, v155
	v_or_b32_e32 v206, 9, v155
	v_or_b32_e32 v207, 10, v155
	v_or_b32_e32 v208, 11, v155
	v_or_b32_e32 v209, 16, v155
	v_or_b32_e32 v210, 17, v155
	v_or_b32_e32 v211, 18, v155
	v_or_b32_e32 v212, 19, v155
	v_or_b32_e32 v213, 24, v155
	v_or_b32_e32 v214, 25, v155
	v_or_b32_e32 v215, 26, v155
	v_or_b32_e32 v216, 27, v155
	v_mov_b32_e32 v161, v2
	v_add_u32_e32 v217, s0, v158
	v_or_b32_e32 v218, 0x800, v1
	v_lshl_or_b32 v162, v154, 11, v5
	v_mov_b32_e32 v163, v2
	v_lshl_or_b32 v164, v156, 12, v7
	v_mov_b32_e32 v165, v2
	v_lshl_or_b32 v166, v3, 14, v9
	v_mov_b32_e32 v167, v2
	s_mov_b32 s0, 0xc2fc0000
	s_mov_b64 s[94:95], 0x4000
	v_lshlrev_b32_e32 v168, 1, v4
	v_lshlrev_b32_e32 v170, 1, v6
	v_add_u32_e32 v219, v10, v7
	s_movk_i32 s1, 0x7fff
	s_mov_b64 s[96:97], 0x80000
	v_mov_b32_e32 v220, 0x42800000
	v_mov_b32_e32 v221, 0x42000000
	v_not_b32_e32 v222, 63
	v_add_u32_e32 v223, v8, v5
	s_mov_b32 s92, s84
	s_branch .LBB0_589

.LBB0_616:
	s_setprio 0
	v_readlane_b32 s74, v255, 12
	v_readlane_b32 s75, v255, 13
	s_load_dwordx2 s[92:93], s[74:75], 0x88
	v_readlane_b32 s91, v255, 14
	v_readlane_b32 s90, v255, 11
